# attention loop: score operand reads issued as (K map0, Q map0, K map1, Q map1) per group so the map-0 MFMA waits for two reads instead of three
# baseline (speedup 1.0000x reference)
; #define LAS __attribute__((address_space(3)))
; __device__ __forceinline__ void dattn_unit(LAS unsigned char* lds, int b, int h, int qb, const bf16* Q, const bf16* K, const bf16* V, bf16* YB, float lam, const float* subg, float oml, int tid) {
;     ...
;             {
;                 const LAS bf16* kp = Ks + (32 * sub + ql) * 72 + hi * 8;
;                 bf16x8 ka = *(const LAS bf16x8*)kp, kb = *(const LAS bf16x8*)(kp + 64 * 72), qa = qsp[0], qb = qsp[4 * 64];
;                 __builtin_amdgcn_sched_group_barrier(0x100, 4, 0);
; #pragma unroll
;                 for (int ks = 0; ks < 4; ++ks) { bf16x8 ka2 = ka, kb2 = kb, qa2 = qa, qb2 = qb;
;                     if (ks < 3) { ka2 = *(const LAS bf16x8*)(kp + (ks + 1) * 16); kb2 = *(const LAS bf16x8*)(kp + 64 * 72 + (ks + 1) * 16); qa2 = qsp[(ks + 1) * 64]; qb2 = qsp[(4 + ks + 1) * 64];
;                         __builtin_amdgcn_sched_group_barrier(0x100, 4, 0); }
;                     s0 = __builtin_amdgcn_mfma_f32_32x32x16_bf16(ka, qa, s0, 0, 0, 0);
;                     s1 = __builtin_amdgcn_mfma_f32_32x32x16_bf16(kb, qb, s1, 0, 0, 0);
;                     __builtin_amdgcn_sched_group_barrier(0x008, 2, 0);
;                     ka = ka2; kb = kb2; qa = qa2; qb = qb2; }
;             }
.LBB0_227:
	v_lshl_add_u64 v[128:129], v[184:185], 0, s[98:99]
	v_lshl_add_u64 v[130:131], v[182:183], 0, s[100:101]
	global_load_dwordx4 v[168:171], v[128:129], off
	global_load_dwordx4 v[172:175], v[128:129], off offset:128
	s_add_i32 s18, s58, 0xffffff50
	global_load_dwordx4 v[164:167], v[130:131], off
	global_load_dwordx4 v[160:163], v[130:131], off offset:16
	s_cmp_gt_i32 s18, s35
	s_cbranch_scc1 .LBB0_226
	s_bitcmp1_b32 s59, 0
	s_cselect_b32 s18, 0x9000, 0
	s_add_i32 s38, s18, 0
	v_add3_u32 v199, s38, v208, v192
	ds_read_b128 v[138:141], v199
	ds_read_b128 v[204:207], v189
	ds_read_b128 v[200:203], v199 offset:9216
	ds_read_b128 v[218:221], v189 offset:4096
	v_xor_b32_e32 v144, 0x80000000, v190
	v_xor_b32_e32 v128, 0x80000000, v191
	v_mov_b32_e32 v145, v144
	v_mov_b64_e32 v[146:147], v[144:145]
	v_mov_b64_e32 v[148:149], v[144:145]
	v_mov_b64_e32 v[150:151], v[144:145]
	v_mov_b64_e32 v[152:153], v[144:145]
	v_mov_b64_e32 v[154:155], v[144:145]
	v_mov_b64_e32 v[156:157], v[144:145]
	v_mov_b64_e32 v[158:159], v[144:145]
	v_mov_b32_e32 v129, v128
	v_mov_b64_e32 v[130:131], v[128:129]
	v_mov_b64_e32 v[132:133], v[128:129]
	v_mov_b64_e32 v[134:135], v[128:129]
	v_mov_b64_e32 v[136:137], v[128:129]
	ds_read_b128 v[222:225], v199 offset:32
	ds_read_b128 v[230:233], v189 offset:1024
	ds_read_b128 v[226:229], v199 offset:9248
	ds_read_b128 v[234:237], v189 offset:5120
	s_waitcnt lgkmcnt(6)
	v_mfma_f32_32x32x16_bf16 v[144:159], v[138:141], v[204:207], v[144:159]
	v_mov_b64_e32 v[142:143], v[128:129]
	v_mov_b64_e32 v[138:139], v[128:129]
	v_mov_b64_e32 v[140:141], v[128:129]
	s_sub_i32 s18, s58, 32
	s_cmp_le_i32 s18, s31
	s_waitcnt lgkmcnt(4)
	v_mfma_f32_32x32x16_bf16 v[128:143], v[200:203], v[218:221], v[128:143]
	ds_read_b128 v[200:203], v199 offset:64
	ds_read_b128 v[218:221], v189 offset:2048
	ds_read_b128 v[204:207], v199 offset:9280
	ds_read_b128 v[238:241], v189 offset:6144
	s_waitcnt lgkmcnt(6)
	v_mfma_f32_32x32x16_bf16 v[144:159], v[222:225], v[230:233], v[144:159]
	s_waitcnt lgkmcnt(4)
	v_mfma_f32_32x32x16_bf16 v[128:143], v[226:229], v[234:237], v[128:143]
	ds_read_b128 v[222:225], v199 offset:96
	ds_read_b128 v[230:233], v189 offset:3072
	ds_read_b128 v[226:229], v199 offset:9312
	ds_read_b128 v[234:237], v189 offset:7168
	s_waitcnt lgkmcnt(6)
	v_mfma_f32_32x32x16_bf16 v[144:159], v[200:203], v[218:221], v[144:159]
	s_cbranch_scc0 .Lqk_diag0
	s_waitcnt lgkmcnt(2)
	v_mfma_f32_32x32x16_bf16 v[144:159], v[222:225], v[230:233], v[144:159]
	v_add3_u32 v219, s38, v193, v192
	ds_read_b128 v[212:215], v219 offset:32256
	ds_read_b128 v[220:223], v219 offset:18432
	v_mfma_f32_32x32x16_bf16 v[128:143], v[204:207], v[238:241], v[128:143]
	s_waitcnt lgkmcnt(2)
	v_mfma_f32_32x32x16_bf16 v[128:143], v[226:229], v[234:237], v[128:143]
	ds_read_b128 v[228:231], v219 offset:23040
	ds_read_b128 v[232:235], v219 offset:23072
	ds_read_b128 v[236:239], v219 offset:27648
	ds_read_b128 v[240:243], v219 offset:27680
	s_nop 1

; #define LAS __attribute__((address_space(3)))
; __device__ __forceinline__ void dattn_unit(LAS unsigned char* lds, int b, int h, int qb, const bf16* Q, const bf16* K, const bf16* V, bf16* YB, float lam, const float* subg, float oml, int tid) {
;     ...
;             if (kvbase + 32 * sub > qmax) continue;
;             const bool need_bm = kvbase + 32 * sub + 31 + 113 > qmin;
;             LAS bf16x8* qsp = qs; asm volatile("" : "+v"(qsp));
;             f32x16 s0, s1;
; #pragma unroll
;             for (int r = 0; r < 16; ++r) { s0[r] = -mref[0]; s1[r] = -mref[1]; }
;             {
;                 const LAS bf16* kp = Ks + (32 * sub + ql) * 72 + hi * 8;
;                 bf16x8 ka = *(const LAS bf16x8*)kp, kb = *(const LAS bf16x8*)(kp + 64 * 72), qa = qsp[0], qb = qsp[4 * 64];
;                 __builtin_amdgcn_sched_group_barrier(0x100, 4, 0);
; #pragma unroll
;                 for (int ks = 0; ks < 4; ++ks) { bf16x8 ka2 = ka, kb2 = kb, qa2 = qa, qb2 = qb;
;                     if (ks < 3) { ka2 = *(const LAS bf16x8*)(kp + (ks + 1) * 16); kb2 = *(const LAS bf16x8*)(kp + 64 * 72 + (ks + 1) * 16); qa2 = qsp[(ks + 1) * 64]; qb2 = qsp[(4 + ks + 1) * 64];
;                         __builtin_amdgcn_sched_group_barrier(0x100, 4, 0); }
;                     s0 = __builtin_amdgcn_mfma_f32_32x32x16_bf16(ka, qa, s0, 0, 0, 0);
;                     s1 = __builtin_amdgcn_mfma_f32_32x32x16_bf16(kb, qb, s1, 0, 0, 0);
;                     __builtin_amdgcn_sched_group_barrier(0x008, 2, 0);
;                     ka = ka2; kb = kb2; qa = qa2; qb = qb2; }
;             }
.LBB0_238:
	s_add_i32 s18, s58, 0xffffff70
	s_cmp_gt_i32 s18, s35
	s_cbranch_scc1 .LBB0_226
	ds_read_b128 v[138:141], v199 offset:4608
	ds_read_b128 v[218:221], v189
	ds_read_b128 v[204:207], v199 offset:13824
	ds_read_b128 v[222:225], v189 offset:4096
	v_xor_b32_e32 v144, 0x80000000, v190
	v_xor_b32_e32 v128, 0x80000000, v191
	v_mov_b32_e32 v145, v144
	v_mov_b64_e32 v[146:147], v[144:145]
	v_mov_b64_e32 v[148:149], v[144:145]
	v_mov_b64_e32 v[150:151], v[144:145]
	v_mov_b64_e32 v[152:153], v[144:145]
	v_mov_b64_e32 v[154:155], v[144:145]
	v_mov_b64_e32 v[156:157], v[144:145]
	v_mov_b64_e32 v[158:159], v[144:145]
	v_mov_b32_e32 v129, v128
	v_mov_b64_e32 v[130:131], v[128:129]
	v_mov_b64_e32 v[132:133], v[128:129]
	v_mov_b64_e32 v[134:135], v[128:129]
	v_mov_b64_e32 v[136:137], v[128:129]
	ds_read_b128 v[226:229], v199 offset:4640
	ds_read_b128 v[234:237], v189 offset:1024
	ds_read_b128 v[230:233], v199 offset:13856
	ds_read_b128 v[238:241], v189 offset:5120
	s_waitcnt lgkmcnt(6)
	v_mfma_f32_32x32x16_bf16 v[144:159], v[138:141], v[218:221], v[144:159]
	v_mov_b64_e32 v[142:143], v[128:129]
	v_mov_b64_e32 v[138:139], v[128:129]
	v_mov_b64_e32 v[140:141], v[128:129]
	s_cmp_le_i32 s58, s31
	s_waitcnt lgkmcnt(4)
	v_mfma_f32_32x32x16_bf16 v[128:143], v[204:207], v[222:225], v[128:143]
	ds_read_b128 v[204:207], v199 offset:4672
	ds_read_b128 v[222:225], v189 offset:2048
	ds_read_b128 v[218:221], v199 offset:13888
	ds_read_b128 v[212:215], v189 offset:6144
	s_waitcnt lgkmcnt(6)
	v_mfma_f32_32x32x16_bf16 v[144:159], v[226:229], v[234:237], v[144:159]
	s_waitcnt lgkmcnt(4)
	v_mfma_f32_32x32x16_bf16 v[128:143], v[230:233], v[238:241], v[128:143]
	ds_read_b128 v[226:229], v199 offset:4704
	ds_read_b128 v[234:237], v189 offset:3072
	ds_read_b128 v[230:233], v199 offset:13920
	ds_read_b128 v[238:241], v189 offset:7168
	s_waitcnt lgkmcnt(6)
	v_mfma_f32_32x32x16_bf16 v[144:159], v[204:207], v[222:225], v[144:159]
	s_cbranch_scc0 .Lqk_diag1
	s_waitcnt lgkmcnt(2)
	v_mfma_f32_32x32x16_bf16 v[144:159], v[226:229], v[234:237], v[144:159]
	v_add3_u32 v243, s38, v193, v192
	ds_read_b128 v[222:225], v243 offset:23104
	ds_read_b128 v[226:229], v243 offset:23136
	v_mfma_f32_32x32x16_bf16 v[128:143], v[218:221], v[212:215], v[128:143]
	s_waitcnt lgkmcnt(2)
	v_mfma_f32_32x32x16_bf16 v[128:143], v[230:233], v[238:241], v[128:143]
	ds_read_b128 v[230:233], v243 offset:27712
	ds_read_b128 v[234:237], v243 offset:27744
	ds_read_b128 v[238:241], v243 offset:32320
	ds_read_b128 v[212:215], v243 offset:18496
	ds_read_b128 v[200:203], v243 offset:18528
	s_nop 1
